# p0_mod: the silu(c) strip loads of chunk k+2 are issued before chunk k's FMAs (one iteration ahead), the loop top only converts and stores them
# speedup vs baseline: 1.0123x; 1.0027x over previous
.LBB0_136:
	s_lshl_b32 s0, s7, 7
	s_add_i32 s6, s7, 1
	s_bitcmp1_b32 s6, 0
	s_cselect_b32 s1, 0x500, 0
	s_addk_i32 s0, 0x80
	s_cmp_lg_u32 s7, 31
	s_cselect_b32 s17, s0, 0xf80
	v_add_u32_e32 v2, s17, v178
	v_add_u32_e32 v4, s1, v177
	s_mov_b64 s[4:5], 0
	v_mov_b32_e32 v5, v1
	v_cmp_gt_u32_e64 s[0:1], 32, v1
	s_cmp_lg_u32 s7, 0
	s_cbranch_scc1 .Lms_have
	v_mov_b32_e32 v38, s9
	v_mov_b32_e32 v39, s8
	v_mov_b32_e32 v40, s71
	v_mov_b32_e32 v41, s69
	v_cndmask_b32_e64 v44, v38, v39, s[0:1]
	v_mov_b32_e32 v42, s70
	v_mov_b32_e32 v43, s68
	v_cndmask_b32_e64 v39, v40, v41, s[0:1]
	v_add_u32_e32 v40, v44, v2
	v_cndmask_b32_e64 v38, v42, v43, s[0:1]
	v_ashrrev_i32_e32 v41, 31, v40
	v_lshl_add_u64 v[38:39], v[40:41], 2, v[38:39]
	global_load_dword v209, v[38:39], off
	v_add_u32_e32 v40, s9, v2
	v_add_u32_e32 v40, 0x4000, v40
	v_ashrrev_i32_e32 v41, 31, v40
	v_lshl_add_u64 v[38:39], v[40:41], 2, s[70:71]
	global_load_dword v210, v[38:39], off
	v_add_u32_e32 v40, 0x4000, v40
	v_ashrrev_i32_e32 v41, 31, v40
	v_lshl_add_u64 v[38:39], v[40:41], 2, s[70:71]
	global_load_dword v211, v[38:39], off
	v_add_u32_e32 v40, 0x4000, v40
	v_ashrrev_i32_e32 v41, 31, v40
	v_lshl_add_u64 v[38:39], v[40:41], 2, s[70:71]
	global_load_dword v212, v[38:39], off
	v_add_u32_e32 v40, 0x4000, v40
	v_ashrrev_i32_e32 v41, 31, v40
	v_lshl_add_u64 v[38:39], v[40:41], 2, s[70:71]
	s_and_saveexec_b64 s[4:5], s[0:1]
	global_load_dword v213, v[38:39], off
	s_mov_b64 exec, s[4:5]
	s_waitcnt vmcnt(0)
.Lms_have:
	v_mul_f32_e32 v50, 0xbfb8aa3b, v209
	v_mul_f32_e32 v51, 0xbfb8aa3b, v210
	v_mul_f32_e32 v52, 0xbfb8aa3b, v211
	v_mul_f32_e32 v53, 0xbfb8aa3b, v212
	v_mul_f32_e32 v54, 0xbfb8aa3b, v213
	v_exp_f32_e32 v50, v50
	v_exp_f32_e32 v51, v51
	v_exp_f32_e32 v52, v52
	v_exp_f32_e32 v53, v53
	v_exp_f32_e32 v54, v54
	v_add_f32_e32 v50, 1.0, v50
	v_add_f32_e32 v51, 1.0, v51
	v_add_f32_e32 v52, 1.0, v52
	v_add_f32_e32 v53, 1.0, v53
	v_add_f32_e32 v54, 1.0, v54
	v_rcp_f32_e32 v50, v50
	v_rcp_f32_e32 v51, v51
	v_rcp_f32_e32 v52, v52
	v_rcp_f32_e32 v53, v53
	v_rcp_f32_e32 v54, v54
	v_mul_f32_e32 v45, v209, v50
	v_mul_f32_e32 v46, v210, v51
	v_mul_f32_e32 v47, v211, v52
	v_mul_f32_e32 v48, v212, v53
	v_mul_f32_e32 v49, v213, v54
	ds_write_b32 v4, v45
	ds_write_b32 v4, v46 offset:16
	ds_write_b32 v4, v47 offset:32
	ds_write_b32 v4, v48 offset:48
	s_and_saveexec_b64 s[4:5], s[0:1]
	ds_write_b32 v4, v49 offset:64
	s_mov_b64 exec, s[4:5]
	s_add_i32 s90, s7, 2
	s_min_u32 s90, s90, 31
	s_lshl_b32 s90, s90, 7
	v_add_u32_e32 v2, s90, v178
	v_mov_b32_e32 v38, s9
	v_mov_b32_e32 v39, s8
	v_mov_b32_e32 v40, s71
	v_mov_b32_e32 v41, s69
	v_cndmask_b32_e64 v44, v38, v39, s[0:1]
	v_mov_b32_e32 v42, s70
	v_mov_b32_e32 v43, s68
	v_cndmask_b32_e64 v39, v40, v41, s[0:1]
	v_add_u32_e32 v40, v44, v2
	v_cndmask_b32_e64 v38, v42, v43, s[0:1]
	v_ashrrev_i32_e32 v41, 31, v40
	v_lshl_add_u64 v[38:39], v[40:41], 2, v[38:39]
	global_load_dword v209, v[38:39], off
	v_add_u32_e32 v40, s9, v2
	v_add_u32_e32 v40, 0x4000, v40
	v_ashrrev_i32_e32 v41, 31, v40
	v_lshl_add_u64 v[38:39], v[40:41], 2, s[70:71]
	global_load_dword v210, v[38:39], off
	v_add_u32_e32 v40, 0x4000, v40
	v_ashrrev_i32_e32 v41, 31, v40
	v_lshl_add_u64 v[38:39], v[40:41], 2, s[70:71]
	global_load_dword v211, v[38:39], off
	v_add_u32_e32 v40, 0x4000, v40
	v_ashrrev_i32_e32 v41, 31, v40
	v_lshl_add_u64 v[38:39], v[40:41], 2, s[70:71]
	global_load_dword v212, v[38:39], off
	v_add_u32_e32 v40, 0x4000, v40
	v_ashrrev_i32_e32 v41, 31, v40
	v_lshl_add_u64 v[38:39], v[40:41], 2, s[70:71]
	s_and_saveexec_b64 s[4:5], s[0:1]
	global_load_dword v213, v[38:39], off
	s_mov_b64 exec, s[4:5]
	s_or_b64 exec, exec, s[4:5]
	s_waitcnt lgkmcnt(0)
	s_and_saveexec_b64 s[0:1], vcc
	s_cbranch_execz .LBB0_140
	v_add_u32_e32 v2, s17, v143
	v_add_u32_e32 v38, 2, v2
	v_mad_i64_i32 v[4:5], s[4:5], v2, s12, v[168:169]
	v_mad_i64_i32 v[42:43], s[4:5], v38, s12, v[168:169]
	global_load_dwordx4 v[38:41], v[4:5], off
	s_nop 0
	global_load_dwordx4 v[42:45], v[42:43], off
	v_or_b32_e32 v4, 4, v2
	v_add_u32_e32 v46, 6, v2
	v_mad_i64_i32 v[4:5], s[4:5], v4, s12, v[168:169]
	v_mad_i64_i32 v[50:51], s[4:5], v46, s12, v[168:169]
	global_load_dwordx4 v[46:49], v[4:5], off
	s_nop 0
	global_load_dwordx4 v[50:53], v[50:51], off
	v_or_b32_e32 v4, 8, v2
	v_add_u32_e32 v54, 10, v2
	s_bitcmp1_b32 s7, 0
	v_mad_i64_i32 v[4:5], s[4:5], v4, s12, v[168:169]
	v_mad_i64_i32 v[58:59], s[4:5], v54, s12, v[168:169]
	s_cselect_b32 s7, 0x500, 0
	global_load_dwordx4 v[54:57], v[4:5], off
	s_nop 0
	global_load_dwordx4 v[58:61], v[58:59], off
	v_or_b32_e32 v4, 12, v2
	v_add_u32_e32 v2, 14, v2
	v_mad_i64_i32 v[4:5], s[4:5], v4, s12, v[168:169]
	v_add_u32_e32 v208, s7, v147
	v_mad_i64_i32 v[66:67], s[4:5], v2, s12, v[168:169]
	ds_read_b128 v[180:183], v208
	ds_read_b128 v[184:187], v208 offset:16
	ds_read_b128 v[188:191], v208 offset:32
	ds_read_b128 v[192:195], v208 offset:48
	global_load_dwordx4 v[62:65], v[4:5], off
	s_nop 0
	global_load_dwordx4 v[66:69], v[66:67], off
	s_waitcnt lgkmcnt(2)
	v_pk_fma_f32 v[200:201], v[34:35], v[184:185], v[74:75] op_sel_hi:[1,0,1]
	s_waitcnt lgkmcnt(1)
	v_pk_fma_f32 v[204:205], v[34:35], v[188:189], v[70:71] op_sel_hi:[1,0,1]
	v_pk_fma_f32 v[206:207], v[36:37], v[188:189], v[72:73] op_sel_hi:[1,0,1]
	ds_read2_b64 v[70:73], v208 offset0:8 offset1:28
	v_mov_b32_e32 v2, v183
	v_pk_fma_f32 v[202:203], v[36:37], v[184:185], v[76:77] op_sel_hi:[1,0,1]
	v_pk_fma_f32 v[4:5], v[34:35], v[2:3], v[114:115] op_sel_hi:[1,0,1]
	v_pk_fma_f32 v[114:115], v[36:37], v[2:3], v[116:117] op_sel_hi:[1,0,1]
	v_mov_b32_e32 v2, v187
	ds_read_b128 v[74:77], v208 offset:160
	v_pk_fma_f32 v[110:111], v[34:35], v[2:3], v[110:111] op_sel_hi:[1,0,1]
	v_pk_fma_f32 v[112:113], v[36:37], v[2:3], v[112:113] op_sel_hi:[1,0,1]
	v_mov_b32_e32 v2, v191
	v_pk_fma_f32 v[116:117], v[34:35], v[2:3], v[126:127] op_sel_hi:[1,0,1]
	v_pk_fma_f32 v[126:127], v[36:37], v[2:3], v[128:129] op_sel_hi:[1,0,1]
	s_waitcnt lgkmcnt(2)
	v_mov_b32_e32 v2, v195
	v_pk_fma_f32 v[196:197], v[34:35], v[180:181], v[82:83] op_sel_hi:[1,0,1]
	v_pk_fma_f32 v[198:199], v[36:37], v[180:181], v[84:85] op_sel_hi:[1,0,1]
	v_pk_fma_f32 v[90:91], v[34:35], v[192:193], v[90:91] op_sel_hi:[1,0,1]
	v_pk_fma_f32 v[92:93], v[36:37], v[192:193], v[92:93] op_sel_hi:[1,0,1]
	v_pk_fma_f32 v[94:95], v[34:35], v[180:181], v[94:95] op_sel:[0,1,0]
	v_pk_fma_f32 v[96:97], v[36:37], v[180:181], v[96:97] op_sel:[0,1,0]
	v_pk_fma_f32 v[86:87], v[34:35], v[184:185], v[86:87] op_sel:[0,1,0]
	v_pk_fma_f32 v[88:89], v[36:37], v[184:185], v[88:89] op_sel:[0,1,0]
	v_pk_fma_f32 v[180:181], v[34:35], v[188:189], v[78:79] op_sel:[0,1,0]
	v_pk_fma_f32 v[184:185], v[36:37], v[188:189], v[80:81] op_sel:[0,1,0]
	v_pk_fma_f32 v[106:107], v[34:35], v[192:193], v[106:107] op_sel:[0,1,0]
	v_pk_fma_f32 v[108:109], v[36:37], v[192:193], v[108:109] op_sel:[0,1,0]
	v_pk_fma_f32 v[102:103], v[34:35], v[182:183], v[102:103] op_sel_hi:[1,0,1]
	v_pk_fma_f32 v[104:105], v[36:37], v[182:183], v[104:105] op_sel_hi:[1,0,1]
	v_pk_fma_f32 v[98:99], v[34:35], v[186:187], v[98:99] op_sel_hi:[1,0,1]
	v_pk_fma_f32 v[100:101], v[36:37], v[186:187], v[100:101] op_sel_hi:[1,0,1]
	v_pk_fma_f32 v[118:119], v[34:35], v[190:191], v[118:119] op_sel_hi:[1,0,1]
	v_pk_fma_f32 v[120:121], v[36:37], v[190:191], v[120:121] op_sel_hi:[1,0,1]
	v_pk_fma_f32 v[122:123], v[34:35], v[194:195], v[122:123] op_sel_hi:[1,0,1]
	v_pk_fma_f32 v[124:125], v[36:37], v[194:195], v[124:125] op_sel_hi:[1,0,1]
	v_pk_fma_f32 v[128:129], v[34:35], v[2:3], v[130:131] op_sel_hi:[1,0,1]
	v_pk_fma_f32 v[130:131], v[36:37], v[2:3], v[132:133] op_sel_hi:[1,0,1]
	s_waitcnt lgkmcnt(1)
	v_pk_fma_f32 v[132:133], v[34:35], v[70:71], v[134:135] op_sel_hi:[1,0,1]
	v_pk_fma_f32 v[134:135], v[36:37], v[70:71], v[136:137] op_sel_hi:[1,0,1]
	v_pk_fma_f32 v[136:137], v[34:35], v[70:71], v[138:139] op_sel:[0,1,0]
	v_pk_fma_f32 v[70:71], v[36:37], v[70:71], v[140:141] op_sel:[0,1,0]
	ds_read_b128 v[34:37], v208 offset:176
	ds_read_b128 v[78:81], v208 offset:192
	ds_read_b128 v[82:85], v208 offset:208
	s_waitcnt lgkmcnt(3)
	v_mov_b32_e32 v2, v77
	v_pk_fma_f32 v[114:115], v[32:33], v[2:3], v[114:115] op_sel_hi:[1,0,1]
	v_pk_fma_f32 v[4:5], v[30:31], v[2:3], v[4:5] op_sel_hi:[1,0,1]
	s_waitcnt lgkmcnt(2)
	v_mov_b32_e32 v2, v37
	v_pk_fma_f32 v[112:113], v[32:33], v[2:3], v[112:113] op_sel_hi:[1,0,1]
	v_pk_fma_f32 v[110:111], v[30:31], v[2:3], v[110:111] op_sel_hi:[1,0,1]
	s_waitcnt lgkmcnt(1)
	v_mov_b32_e32 v2, v81
	s_waitcnt lgkmcnt(0)
	v_pk_fma_f32 v[92:93], v[32:33], v[82:83], v[92:93] op_sel_hi:[1,0,1]
	v_pk_fma_f32 v[90:91], v[30:31], v[82:83], v[90:91] op_sel_hi:[1,0,1]
	v_pk_fma_f32 v[108:109], v[32:33], v[82:83], v[108:109] op_sel:[0,1,0]
	v_pk_fma_f32 v[82:83], v[30:31], v[82:83], v[106:107] op_sel:[0,1,0]
	v_pk_fma_f32 v[106:107], v[32:33], v[80:81], v[120:121] op_sel_hi:[1,0,1]
	v_pk_fma_f32 v[120:121], v[32:33], v[84:85], v[124:125] op_sel_hi:[1,0,1]
	v_pk_fma_f32 v[124:125], v[32:33], v[2:3], v[126:127] op_sel_hi:[1,0,1]
	v_pk_fma_f32 v[116:117], v[30:31], v[2:3], v[116:117] op_sel_hi:[1,0,1]
	v_mov_b32_e32 v2, v85
	v_pk_fma_f32 v[138:139], v[32:33], v[74:75], v[198:199] op_sel_hi:[1,0,1]
	v_pk_fma_f32 v[140:141], v[30:31], v[74:75], v[196:197] op_sel_hi:[1,0,1]
	v_pk_fma_f32 v[182:183], v[32:33], v[34:35], v[202:203] op_sel_hi:[1,0,1]
	v_pk_fma_f32 v[186:187], v[30:31], v[34:35], v[200:201] op_sel_hi:[1,0,1]
	v_pk_fma_f32 v[188:189], v[32:33], v[78:79], v[206:207] op_sel_hi:[1,0,1]
	v_pk_fma_f32 v[190:191], v[30:31], v[78:79], v[204:205] op_sel_hi:[1,0,1]
	v_pk_fma_f32 v[96:97], v[32:33], v[74:75], v[96:97] op_sel:[0,1,0]
	v_pk_fma_f32 v[94:95], v[30:31], v[74:75], v[94:95] op_sel:[0,1,0]
	v_pk_fma_f32 v[88:89], v[32:33], v[34:35], v[88:89] op_sel:[0,1,0]
	v_pk_fma_f32 v[86:87], v[30:31], v[34:35], v[86:87] op_sel:[0,1,0]
	v_pk_fma_f32 v[184:185], v[32:33], v[78:79], v[184:185] op_sel:[0,1,0]
	v_pk_fma_f32 v[180:181], v[30:31], v[78:79], v[180:181] op_sel:[0,1,0]
	v_pk_fma_f32 v[104:105], v[32:33], v[76:77], v[104:105] op_sel_hi:[1,0,1]
	v_pk_fma_f32 v[102:103], v[30:31], v[76:77], v[102:103] op_sel_hi:[1,0,1]
	v_pk_fma_f32 v[100:101], v[32:33], v[36:37], v[100:101] op_sel_hi:[1,0,1]
	v_pk_fma_f32 v[98:99], v[30:31], v[36:37], v[98:99] op_sel_hi:[1,0,1]
	v_pk_fma_f32 v[118:119], v[30:31], v[80:81], v[118:119] op_sel_hi:[1,0,1]
	v_pk_fma_f32 v[122:123], v[30:31], v[84:85], v[122:123] op_sel_hi:[1,0,1]
	v_pk_fma_f32 v[84:85], v[32:33], v[2:3], v[130:131] op_sel_hi:[1,0,1]
	v_pk_fma_f32 v[126:127], v[30:31], v[2:3], v[128:129] op_sel_hi:[1,0,1]
	v_pk_fma_f32 v[128:129], v[32:33], v[72:73], v[134:135] op_sel_hi:[1,0,1]
	v_pk_fma_f32 v[130:131], v[30:31], v[72:73], v[132:133] op_sel_hi:[1,0,1]
	v_pk_fma_f32 v[132:133], v[32:33], v[72:73], v[70:71] op_sel:[0,1,0]
	v_pk_fma_f32 v[134:135], v[30:31], v[72:73], v[136:137] op_sel:[0,1,0]
	ds_read_b128 v[30:33], v208 offset:320
	ds_read_b128 v[34:37], v208 offset:336
	ds_read_b128 v[70:73], v208 offset:352
	ds_read_b128 v[74:77], v208 offset:368
	ds_read2_b64 v[78:81], v208 offset0:48 offset1:68
	s_waitcnt lgkmcnt(4)
	v_mov_b32_e32 v2, v33
	v_pk_fma_f32 v[136:137], v[26:27], v[30:31], v[140:141] op_sel_hi:[1,0,1]
	v_pk_fma_f32 v[138:139], v[28:29], v[30:31], v[138:139] op_sel_hi:[1,0,1]
	v_pk_fma_f32 v[94:95], v[26:27], v[30:31], v[94:95] op_sel:[0,1,0]
	v_pk_fma_f32 v[96:97], v[28:29], v[30:31], v[96:97] op_sel:[0,1,0]
	v_pk_fma_f32 v[102:103], v[26:27], v[32:33], v[102:103] op_sel_hi:[1,0,1]
	v_pk_fma_f32 v[104:105], v[28:29], v[32:33], v[104:105] op_sel_hi:[1,0,1]
	v_pk_fma_f32 v[4:5], v[26:27], v[2:3], v[4:5] op_sel_hi:[1,0,1]
	v_pk_fma_f32 v[114:115], v[28:29], v[2:3], v[114:115] op_sel_hi:[1,0,1]
	s_waitcnt lgkmcnt(3)
	v_mov_b32_e32 v2, v37
	ds_read_b128 v[30:33], v208 offset:480
	v_pk_fma_f32 v[110:111], v[26:27], v[2:3], v[110:111] op_sel_hi:[1,0,1]
	v_pk_fma_f32 v[112:113], v[28:29], v[2:3], v[112:113] op_sel_hi:[1,0,1]
	s_waitcnt lgkmcnt(3)
	v_mov_b32_e32 v2, v73
	s_waitcnt lgkmcnt(2)
	v_pk_fma_f32 v[90:91], v[26:27], v[74:75], v[90:91] op_sel_hi:[1,0,1]
	v_pk_fma_f32 v[92:93], v[28:29], v[74:75], v[92:93] op_sel_hi:[1,0,1]
	v_pk_fma_f32 v[82:83], v[26:27], v[74:75], v[82:83] op_sel:[0,1,0]
	v_pk_fma_f32 v[74:75], v[28:29], v[74:75], v[108:109] op_sel:[0,1,0]
	v_pk_fma_f32 v[108:109], v[26:27], v[72:73], v[118:119] op_sel_hi:[1,0,1]
	v_pk_fma_f32 v[118:119], v[26:27], v[76:77], v[122:123] op_sel_hi:[1,0,1]
	v_pk_fma_f32 v[116:117], v[26:27], v[2:3], v[116:117] op_sel_hi:[1,0,1]
	v_pk_fma_f32 v[122:123], v[28:29], v[2:3], v[124:125] op_sel_hi:[1,0,1]
	v_mov_b32_e32 v2, v77
	v_pk_fma_f32 v[140:141], v[26:27], v[34:35], v[186:187] op_sel_hi:[1,0,1]
	v_pk_fma_f32 v[182:183], v[28:29], v[34:35], v[182:183] op_sel_hi:[1,0,1]
	v_pk_fma_f32 v[186:187], v[26:27], v[70:71], v[190:191] op_sel_hi:[1,0,1]
	v_pk_fma_f32 v[188:189], v[28:29], v[70:71], v[188:189] op_sel_hi:[1,0,1]
	v_pk_fma_f32 v[86:87], v[26:27], v[34:35], v[86:87] op_sel:[0,1,0]
	v_pk_fma_f32 v[88:89], v[28:29], v[34:35], v[88:89] op_sel:[0,1,0]
	v_pk_fma_f32 v[180:181], v[26:27], v[70:71], v[180:181] op_sel:[0,1,0]
	v_pk_fma_f32 v[184:185], v[28:29], v[70:71], v[184:185] op_sel:[0,1,0]
	v_pk_fma_f32 v[98:99], v[26:27], v[36:37], v[98:99] op_sel_hi:[1,0,1]
	v_pk_fma_f32 v[100:101], v[28:29], v[36:37], v[100:101] op_sel_hi:[1,0,1]
	v_pk_fma_f32 v[106:107], v[28:29], v[72:73], v[106:107] op_sel_hi:[1,0,1]
	v_pk_fma_f32 v[120:121], v[28:29], v[76:77], v[120:121] op_sel_hi:[1,0,1]
	v_pk_fma_f32 v[76:77], v[26:27], v[2:3], v[126:127] op_sel_hi:[1,0,1]
	v_pk_fma_f32 v[84:85], v[28:29], v[2:3], v[84:85] op_sel_hi:[1,0,1]
	s_waitcnt lgkmcnt(1)
	v_pk_fma_f32 v[124:125], v[26:27], v[78:79], v[130:131] op_sel_hi:[1,0,1]
	v_pk_fma_f32 v[126:127], v[28:29], v[78:79], v[128:129] op_sel_hi:[1,0,1]
	v_pk_fma_f32 v[128:129], v[26:27], v[78:79], v[134:135] op_sel:[0,1,0]
	v_pk_fma_f32 v[78:79], v[28:29], v[78:79], v[132:133] op_sel:[0,1,0]
	ds_read_b128 v[26:29], v208 offset:496
	ds_read_b128 v[34:37], v208 offset:512
	ds_read_b128 v[70:73], v208 offset:528
	s_waitcnt lgkmcnt(3)
	v_mov_b32_e32 v2, v33
	v_pk_fma_f32 v[114:115], v[24:25], v[2:3], v[114:115] op_sel_hi:[1,0,1]
	v_pk_fma_f32 v[4:5], v[22:23], v[2:3], v[4:5] op_sel_hi:[1,0,1]
	s_waitcnt lgkmcnt(2)
	v_mov_b32_e32 v2, v29
	v_pk_fma_f32 v[112:113], v[24:25], v[2:3], v[112:113] op_sel_hi:[1,0,1]
	v_pk_fma_f32 v[110:111], v[22:23], v[2:3], v[110:111] op_sel_hi:[1,0,1]
	s_waitcnt lgkmcnt(1)
	v_mov_b32_e32 v2, v37
	v_pk_fma_f32 v[122:123], v[24:25], v[2:3], v[122:123] op_sel_hi:[1,0,1]
	v_pk_fma_f32 v[116:117], v[22:23], v[2:3], v[116:117] op_sel_hi:[1,0,1]
	s_waitcnt lgkmcnt(0)
	v_mov_b32_e32 v2, v73
	v_pk_fma_f32 v[130:131], v[24:25], v[30:31], v[138:139] op_sel_hi:[1,0,1]
	v_pk_fma_f32 v[132:133], v[22:23], v[30:31], v[136:137] op_sel_hi:[1,0,1]
	v_pk_fma_f32 v[134:135], v[24:25], v[26:27], v[182:183] op_sel_hi:[1,0,1]
	v_pk_fma_f32 v[136:137], v[22:23], v[26:27], v[140:141] op_sel_hi:[1,0,1]
	v_pk_fma_f32 v[138:139], v[24:25], v[34:35], v[188:189] op_sel_hi:[1,0,1]
	v_pk_fma_f32 v[140:141], v[22:23], v[34:35], v[186:187] op_sel_hi:[1,0,1]
	v_pk_fma_f32 v[92:93], v[24:25], v[70:71], v[92:93] op_sel_hi:[1,0,1]
	v_pk_fma_f32 v[90:91], v[22:23], v[70:71], v[90:91] op_sel_hi:[1,0,1]
	v_pk_fma_f32 v[96:97], v[24:25], v[30:31], v[96:97] op_sel:[0,1,0]
	v_pk_fma_f32 v[94:95], v[22:23], v[30:31], v[94:95] op_sel:[0,1,0]
	v_pk_fma_f32 v[88:89], v[24:25], v[26:27], v[88:89] op_sel:[0,1,0]
	v_pk_fma_f32 v[86:87], v[22:23], v[26:27], v[86:87] op_sel:[0,1,0]
	v_pk_fma_f32 v[182:183], v[24:25], v[34:35], v[184:185] op_sel:[0,1,0]
	v_pk_fma_f32 v[180:181], v[22:23], v[34:35], v[180:181] op_sel:[0,1,0]
	v_pk_fma_f32 v[74:75], v[24:25], v[70:71], v[74:75] op_sel:[0,1,0]
	v_pk_fma_f32 v[82:83], v[22:23], v[70:71], v[82:83] op_sel:[0,1,0]
	v_pk_fma_f32 v[104:105], v[24:25], v[32:33], v[104:105] op_sel_hi:[1,0,1]
	v_pk_fma_f32 v[102:103], v[22:23], v[32:33], v[102:103] op_sel_hi:[1,0,1]
	v_pk_fma_f32 v[100:101], v[24:25], v[28:29], v[100:101] op_sel_hi:[1,0,1]
	v_pk_fma_f32 v[98:99], v[22:23], v[28:29], v[98:99] op_sel_hi:[1,0,1]
	v_pk_fma_f32 v[106:107], v[24:25], v[36:37], v[106:107] op_sel_hi:[1,0,1]
	v_pk_fma_f32 v[108:109], v[22:23], v[36:37], v[108:109] op_sel_hi:[1,0,1]
	v_pk_fma_f32 v[120:121], v[24:25], v[72:73], v[120:121] op_sel_hi:[1,0,1]
	v_pk_fma_f32 v[118:119], v[22:23], v[72:73], v[118:119] op_sel_hi:[1,0,1]
	v_pk_fma_f32 v[84:85], v[24:25], v[2:3], v[84:85] op_sel_hi:[1,0,1]
	v_pk_fma_f32 v[76:77], v[22:23], v[2:3], v[76:77] op_sel_hi:[1,0,1]
	v_pk_fma_f32 v[126:127], v[24:25], v[80:81], v[126:127] op_sel_hi:[1,0,1]
	v_pk_fma_f32 v[124:125], v[22:23], v[80:81], v[124:125] op_sel_hi:[1,0,1]
	v_pk_fma_f32 v[78:79], v[24:25], v[80:81], v[78:79] op_sel:[0,1,0]
	v_pk_fma_f32 v[80:81], v[22:23], v[80:81], v[128:129] op_sel:[0,1,0]
	ds_read_b128 v[22:25], v208 offset:640
	ds_read_b128 v[26:29], v208 offset:656
	ds_read_b128 v[30:33], v208 offset:672
	ds_read_b128 v[34:37], v208 offset:688
	ds_read2_b64 v[70:73], v208 offset0:88 offset1:108
	s_waitcnt lgkmcnt(4)
	v_mov_b32_e32 v2, v25
	v_pk_fma_f32 v[128:129], v[18:19], v[22:23], v[132:133] op_sel_hi:[1,0,1]
	v_pk_fma_f32 v[130:131], v[20:21], v[22:23], v[130:131] op_sel_hi:[1,0,1]
	s_waitcnt lgkmcnt(1)
	v_pk_fma_f32 v[90:91], v[18:19], v[34:35], v[90:91] op_sel_hi:[1,0,1]
	v_pk_fma_f32 v[92:93], v[20:21], v[34:35], v[92:93] op_sel_hi:[1,0,1]
	v_pk_fma_f32 v[94:95], v[18:19], v[22:23], v[94:95] op_sel:[0,1,0]
	v_pk_fma_f32 v[96:97], v[20:21], v[22:23], v[96:97] op_sel:[0,1,0]
	v_pk_fma_f32 v[82:83], v[18:19], v[34:35], v[82:83] op_sel:[0,1,0]
	v_pk_fma_f32 v[34:35], v[20:21], v[34:35], v[74:75] op_sel:[0,1,0]
	v_pk_fma_f32 v[74:75], v[18:19], v[24:25], v[102:103] op_sel_hi:[1,0,1]
	v_pk_fma_f32 v[102:103], v[20:21], v[24:25], v[104:105] op_sel_hi:[1,0,1]
	v_pk_fma_f32 v[4:5], v[18:19], v[2:3], v[4:5] op_sel_hi:[1,0,1]
	v_pk_fma_f32 v[114:115], v[20:21], v[2:3], v[114:115] op_sel_hi:[1,0,1]
	v_mov_b32_e32 v2, v29
	ds_read_b128 v[22:25], v208 offset:800
	v_pk_fma_f32 v[110:111], v[18:19], v[2:3], v[110:111] op_sel_hi:[1,0,1]
	v_pk_fma_f32 v[112:113], v[20:21], v[2:3], v[112:113] op_sel_hi:[1,0,1]
	v_mov_b32_e32 v2, v33
	v_pk_fma_f32 v[104:105], v[18:19], v[32:33], v[108:109] op_sel_hi:[1,0,1]
	v_pk_fma_f32 v[108:109], v[18:19], v[36:37], v[118:119] op_sel_hi:[1,0,1]
	v_pk_fma_f32 v[118:119], v[20:21], v[36:37], v[120:121] op_sel_hi:[1,0,1]
	v_pk_fma_f32 v[116:117], v[18:19], v[2:3], v[116:117] op_sel_hi:[1,0,1]
	v_pk_fma_f32 v[120:121], v[20:21], v[2:3], v[122:123] op_sel_hi:[1,0,1]
	v_mov_b32_e32 v2, v37
	v_pk_fma_f32 v[132:133], v[18:19], v[26:27], v[136:137] op_sel_hi:[1,0,1]
	v_pk_fma_f32 v[134:135], v[20:21], v[26:27], v[134:135] op_sel_hi:[1,0,1]
	v_pk_fma_f32 v[136:137], v[18:19], v[30:31], v[140:141] op_sel_hi:[1,0,1]
	v_pk_fma_f32 v[138:139], v[20:21], v[30:31], v[138:139] op_sel_hi:[1,0,1]
	v_pk_fma_f32 v[86:87], v[18:19], v[26:27], v[86:87] op_sel:[0,1,0]
	v_pk_fma_f32 v[88:89], v[20:21], v[26:27], v[88:89] op_sel:[0,1,0]
	v_pk_fma_f32 v[140:141], v[18:19], v[30:31], v[180:181] op_sel:[0,1,0]
	v_pk_fma_f32 v[180:181], v[20:21], v[30:31], v[182:183] op_sel:[0,1,0]
	v_pk_fma_f32 v[98:99], v[18:19], v[28:29], v[98:99] op_sel_hi:[1,0,1]
	v_pk_fma_f32 v[100:101], v[20:21], v[28:29], v[100:101] op_sel_hi:[1,0,1]
	v_pk_fma_f32 v[106:107], v[20:21], v[32:33], v[106:107] op_sel_hi:[1,0,1]
	v_pk_fma_f32 v[36:37], v[18:19], v[2:3], v[76:77] op_sel_hi:[1,0,1]
	v_pk_fma_f32 v[76:77], v[20:21], v[2:3], v[84:85] op_sel_hi:[1,0,1]
	s_waitcnt lgkmcnt(1)
	v_pk_fma_f32 v[84:85], v[18:19], v[70:71], v[124:125] op_sel_hi:[1,0,1]
	v_pk_fma_f32 v[122:123], v[20:21], v[70:71], v[126:127] op_sel_hi:[1,0,1]
	v_pk_fma_f32 v[80:81], v[18:19], v[70:71], v[80:81] op_sel:[0,1,0]
	v_pk_fma_f32 v[70:71], v[20:21], v[70:71], v[78:79] op_sel:[0,1,0]
	ds_read_b128 v[18:21], v208 offset:816
	ds_read_b128 v[26:29], v208 offset:832
	ds_read_b128 v[30:33], v208 offset:848
	s_waitcnt lgkmcnt(3)
	v_mov_b32_e32 v2, v25
	v_pk_fma_f32 v[114:115], v[16:17], v[2:3], v[114:115] op_sel_hi:[1,0,1]
	v_pk_fma_f32 v[4:5], v[14:15], v[2:3], v[4:5] op_sel_hi:[1,0,1]
	s_waitcnt lgkmcnt(2)
	v_mov_b32_e32 v2, v21
	v_pk_fma_f32 v[112:113], v[16:17], v[2:3], v[112:113] op_sel_hi:[1,0,1]
	v_pk_fma_f32 v[110:111], v[14:15], v[2:3], v[110:111] op_sel_hi:[1,0,1]
	s_waitcnt lgkmcnt(1)
	v_mov_b32_e32 v2, v29
	v_pk_fma_f32 v[120:121], v[16:17], v[2:3], v[120:121] op_sel_hi:[1,0,1]
	v_pk_fma_f32 v[116:117], v[14:15], v[2:3], v[116:117] op_sel_hi:[1,0,1]
	s_waitcnt lgkmcnt(0)
	v_mov_b32_e32 v2, v33
	v_pk_fma_f32 v[78:79], v[16:17], v[22:23], v[130:131] op_sel_hi:[1,0,1]
	v_pk_fma_f32 v[124:125], v[14:15], v[22:23], v[128:129] op_sel_hi:[1,0,1]
	v_pk_fma_f32 v[126:127], v[16:17], v[18:19], v[134:135] op_sel_hi:[1,0,1]
	v_pk_fma_f32 v[128:129], v[14:15], v[18:19], v[132:133] op_sel_hi:[1,0,1]
	v_pk_fma_f32 v[130:131], v[16:17], v[26:27], v[138:139] op_sel_hi:[1,0,1]
	v_pk_fma_f32 v[132:133], v[14:15], v[26:27], v[136:137] op_sel_hi:[1,0,1]
	v_pk_fma_f32 v[92:93], v[16:17], v[30:31], v[92:93] op_sel_hi:[1,0,1]
	v_pk_fma_f32 v[90:91], v[14:15], v[30:31], v[90:91] op_sel_hi:[1,0,1]
	v_pk_fma_f32 v[96:97], v[16:17], v[22:23], v[96:97] op_sel:[0,1,0]
	v_pk_fma_f32 v[94:95], v[14:15], v[22:23], v[94:95] op_sel:[0,1,0]
	v_pk_fma_f32 v[88:89], v[16:17], v[18:19], v[88:89] op_sel:[0,1,0]
	v_pk_fma_f32 v[86:87], v[14:15], v[18:19], v[86:87] op_sel:[0,1,0]
	v_pk_fma_f32 v[134:135], v[16:17], v[26:27], v[180:181] op_sel:[0,1,0]
	v_pk_fma_f32 v[136:137], v[14:15], v[26:27], v[140:141] op_sel:[0,1,0]
	v_pk_fma_f32 v[34:35], v[16:17], v[30:31], v[34:35] op_sel:[0,1,0]
	v_pk_fma_f32 v[82:83], v[14:15], v[30:31], v[82:83] op_sel:[0,1,0]
	v_pk_fma_f32 v[102:103], v[16:17], v[24:25], v[102:103] op_sel_hi:[1,0,1]
	v_pk_fma_f32 v[74:75], v[14:15], v[24:25], v[74:75] op_sel_hi:[1,0,1]
	v_pk_fma_f32 v[100:101], v[16:17], v[20:21], v[100:101] op_sel_hi:[1,0,1]
	v_pk_fma_f32 v[98:99], v[14:15], v[20:21], v[98:99] op_sel_hi:[1,0,1]
	v_pk_fma_f32 v[106:107], v[16:17], v[28:29], v[106:107] op_sel_hi:[1,0,1]
	v_pk_fma_f32 v[104:105], v[14:15], v[28:29], v[104:105] op_sel_hi:[1,0,1]
	v_pk_fma_f32 v[118:119], v[16:17], v[32:33], v[118:119] op_sel_hi:[1,0,1]
	v_pk_fma_f32 v[108:109], v[14:15], v[32:33], v[108:109] op_sel_hi:[1,0,1]
	v_pk_fma_f32 v[76:77], v[16:17], v[2:3], v[76:77] op_sel_hi:[1,0,1]
	v_pk_fma_f32 v[36:37], v[14:15], v[2:3], v[36:37] op_sel_hi:[1,0,1]
	v_pk_fma_f32 v[122:123], v[16:17], v[72:73], v[122:123] op_sel_hi:[1,0,1]
	v_pk_fma_f32 v[84:85], v[14:15], v[72:73], v[84:85] op_sel_hi:[1,0,1]
	v_pk_fma_f32 v[70:71], v[16:17], v[72:73], v[70:71] op_sel:[0,1,0]
	v_pk_fma_f32 v[72:73], v[14:15], v[72:73], v[80:81] op_sel:[0,1,0]
	ds_read_b128 v[14:17], v208 offset:960
	ds_read_b128 v[18:21], v208 offset:976
	ds_read_b128 v[22:25], v208 offset:992
	ds_read_b128 v[26:29], v208 offset:1008
	ds_read2_b64 v[30:33], v208 offset0:128 offset1:148
	s_waitcnt lgkmcnt(4)
	v_mov_b32_e32 v2, v17
	v_pk_fma_f32 v[80:81], v[10:11], v[14:15], v[124:125] op_sel_hi:[1,0,1]
	v_pk_fma_f32 v[78:79], v[12:13], v[14:15], v[78:79] op_sel_hi:[1,0,1]
	s_waitcnt lgkmcnt(3)
	v_pk_fma_f32 v[124:125], v[10:11], v[18:19], v[128:129] op_sel_hi:[1,0,1]
	s_waitcnt lgkmcnt(2)
	v_pk_fma_f32 v[128:129], v[10:11], v[22:23], v[132:133] op_sel_hi:[1,0,1]
	s_waitcnt lgkmcnt(1)
	v_pk_fma_f32 v[90:91], v[10:11], v[26:27], v[90:91] op_sel_hi:[1,0,1]
	v_pk_fma_f32 v[92:93], v[12:13], v[26:27], v[92:93] op_sel_hi:[1,0,1]
	v_pk_fma_f32 v[94:95], v[10:11], v[14:15], v[94:95] op_sel:[0,1,0]
	v_pk_fma_f32 v[96:97], v[12:13], v[14:15], v[96:97] op_sel:[0,1,0]
	v_pk_fma_f32 v[132:133], v[10:11], v[22:23], v[136:137] op_sel:[0,1,0]
	v_pk_fma_f32 v[136:137], v[10:11], v[26:27], v[82:83] op_sel:[0,1,0]
	v_pk_fma_f32 v[26:27], v[12:13], v[26:27], v[34:35] op_sel:[0,1,0]
	v_pk_fma_f32 v[34:35], v[10:11], v[16:17], v[74:75] op_sel_hi:[1,0,1]
	v_pk_fma_f32 v[102:103], v[12:13], v[16:17], v[102:103] op_sel_hi:[1,0,1]
	v_pk_fma_f32 v[4:5], v[10:11], v[2:3], v[4:5] op_sel_hi:[1,0,1]
	v_pk_fma_f32 v[114:115], v[12:13], v[2:3], v[114:115] op_sel_hi:[1,0,1]
	v_mov_b32_e32 v2, v21
	ds_read_b128 v[14:17], v208 offset:1120
	v_pk_fma_f32 v[110:111], v[10:11], v[2:3], v[110:111] op_sel_hi:[1,0,1]
	v_pk_fma_f32 v[112:113], v[12:13], v[2:3], v[112:113] op_sel_hi:[1,0,1]
	v_mov_b32_e32 v2, v25
	v_pk_fma_f32 v[184:185], v[10:11], v[2:3], v[116:117] op_sel_hi:[1,0,1]
	v_pk_fma_f32 v[186:187], v[12:13], v[2:3], v[120:121] op_sel_hi:[1,0,1]
	v_mov_b32_e32 v2, v29
	v_pk_fma_f32 v[126:127], v[12:13], v[18:19], v[126:127] op_sel_hi:[1,0,1]
	v_pk_fma_f32 v[130:131], v[12:13], v[22:23], v[130:131] op_sel_hi:[1,0,1]
	v_pk_fma_f32 v[86:87], v[10:11], v[18:19], v[86:87] op_sel:[0,1,0]
	v_pk_fma_f32 v[88:89], v[12:13], v[18:19], v[88:89] op_sel:[0,1,0]
	v_pk_fma_f32 v[134:135], v[12:13], v[22:23], v[134:135] op_sel:[0,1,0]
	v_pk_fma_f32 v[98:99], v[10:11], v[20:21], v[98:99] op_sel_hi:[1,0,1]
	v_pk_fma_f32 v[100:101], v[12:13], v[20:21], v[100:101] op_sel_hi:[1,0,1]
	v_pk_fma_f32 v[138:139], v[10:11], v[24:25], v[104:105] op_sel_hi:[1,0,1]
	v_pk_fma_f32 v[140:141], v[12:13], v[24:25], v[106:107] op_sel_hi:[1,0,1]
	v_pk_fma_f32 v[180:181], v[10:11], v[28:29], v[108:109] op_sel_hi:[1,0,1]
	v_pk_fma_f32 v[182:183], v[12:13], v[28:29], v[118:119] op_sel_hi:[1,0,1]
	v_pk_fma_f32 v[28:29], v[10:11], v[2:3], v[36:37] op_sel_hi:[1,0,1]
	v_pk_fma_f32 v[36:37], v[12:13], v[2:3], v[76:77] op_sel_hi:[1,0,1]
	s_waitcnt lgkmcnt(1)
	v_pk_fma_f32 v[188:189], v[10:11], v[30:31], v[84:85] op_sel_hi:[1,0,1]
	v_pk_fma_f32 v[190:191], v[12:13], v[30:31], v[122:123] op_sel_hi:[1,0,1]
	v_pk_fma_f32 v[192:193], v[10:11], v[30:31], v[72:73] op_sel:[0,1,0]
	v_pk_fma_f32 v[30:31], v[12:13], v[30:31], v[70:71] op_sel:[0,1,0]
	ds_read_b128 v[10:13], v208 offset:1136
	ds_read_b128 v[18:21], v208 offset:1152
	ds_read_b128 v[22:25], v208 offset:1168
	s_waitcnt lgkmcnt(3)
	v_mov_b32_e32 v2, v17
	v_pk_fma_f32 v[116:117], v[8:9], v[2:3], v[114:115] op_sel_hi:[1,0,1]
	v_pk_fma_f32 v[114:115], v[6:7], v[2:3], v[4:5] op_sel_hi:[1,0,1]
	s_waitcnt lgkmcnt(2)
	v_mov_b32_e32 v2, v13
	v_pk_fma_f32 v[112:113], v[8:9], v[2:3], v[112:113] op_sel_hi:[1,0,1]
	v_pk_fma_f32 v[110:111], v[6:7], v[2:3], v[110:111] op_sel_hi:[1,0,1]
	s_waitcnt lgkmcnt(1)
	v_mov_b32_e32 v2, v21
	v_pk_fma_f32 v[76:77], v[8:9], v[10:11], v[126:127] op_sel_hi:[1,0,1]
	v_pk_fma_f32 v[70:71], v[6:7], v[18:19], v[128:129] op_sel_hi:[1,0,1]
	v_pk_fma_f32 v[128:129], v[8:9], v[2:3], v[186:187] op_sel_hi:[1,0,1]
	v_pk_fma_f32 v[126:127], v[6:7], v[2:3], v[184:185] op_sel_hi:[1,0,1]
	s_waitcnt lgkmcnt(0)
	v_mov_b32_e32 v2, v25
	v_pk_fma_f32 v[84:85], v[8:9], v[14:15], v[78:79] op_sel_hi:[1,0,1]
	v_pk_fma_f32 v[82:83], v[6:7], v[14:15], v[80:81] op_sel_hi:[1,0,1]
	v_pk_fma_f32 v[74:75], v[6:7], v[10:11], v[124:125] op_sel_hi:[1,0,1]
	v_pk_fma_f32 v[72:73], v[8:9], v[18:19], v[130:131] op_sel_hi:[1,0,1]
	v_pk_fma_f32 v[92:93], v[8:9], v[22:23], v[92:93] op_sel_hi:[1,0,1]
	v_pk_fma_f32 v[90:91], v[6:7], v[22:23], v[90:91] op_sel_hi:[1,0,1]
	v_pk_fma_f32 v[96:97], v[8:9], v[14:15], v[96:97] op_sel:[0,1,0]
	v_pk_fma_f32 v[94:95], v[6:7], v[14:15], v[94:95] op_sel:[0,1,0]
	v_pk_fma_f32 v[88:89], v[8:9], v[10:11], v[88:89] op_sel:[0,1,0]
	v_pk_fma_f32 v[86:87], v[6:7], v[10:11], v[86:87] op_sel:[0,1,0]
	v_pk_fma_f32 v[80:81], v[8:9], v[18:19], v[134:135] op_sel:[0,1,0]
	v_pk_fma_f32 v[78:79], v[6:7], v[18:19], v[132:133] op_sel:[0,1,0]
	v_pk_fma_f32 v[108:109], v[8:9], v[22:23], v[26:27] op_sel:[0,1,0]
	v_pk_fma_f32 v[106:107], v[6:7], v[22:23], v[136:137] op_sel:[0,1,0]
	v_pk_fma_f32 v[104:105], v[8:9], v[16:17], v[102:103] op_sel_hi:[1,0,1]
	v_pk_fma_f32 v[102:103], v[6:7], v[16:17], v[34:35] op_sel_hi:[1,0,1]
	v_pk_fma_f32 v[100:101], v[8:9], v[12:13], v[100:101] op_sel_hi:[1,0,1]
	v_pk_fma_f32 v[98:99], v[6:7], v[12:13], v[98:99] op_sel_hi:[1,0,1]
	v_pk_fma_f32 v[120:121], v[8:9], v[20:21], v[140:141] op_sel_hi:[1,0,1]
	v_pk_fma_f32 v[118:119], v[6:7], v[20:21], v[138:139] op_sel_hi:[1,0,1]
	v_pk_fma_f32 v[124:125], v[8:9], v[24:25], v[182:183] op_sel_hi:[1,0,1]
	v_pk_fma_f32 v[122:123], v[6:7], v[24:25], v[180:181] op_sel_hi:[1,0,1]
	v_pk_fma_f32 v[132:133], v[8:9], v[2:3], v[36:37] op_sel_hi:[1,0,1]
	v_pk_fma_f32 v[130:131], v[6:7], v[2:3], v[28:29] op_sel_hi:[1,0,1]
	v_pk_fma_f32 v[136:137], v[8:9], v[32:33], v[190:191] op_sel_hi:[1,0,1]
	v_pk_fma_f32 v[134:135], v[6:7], v[32:33], v[188:189] op_sel_hi:[1,0,1]
	v_pk_fma_f32 v[140:141], v[8:9], v[32:33], v[30:31] op_sel:[0,1,0]
	v_pk_fma_f32 v[138:139], v[6:7], v[32:33], v[192:193] op_sel:[0,1,0]
	s_waitcnt vmcnt(0)
	v_mov_b64_e32 v[6:7], v[66:67]
	v_mov_b64_e32 v[10:11], v[62:63]
	v_mov_b64_e32 v[14:15], v[58:59]
	v_mov_b64_e32 v[18:19], v[54:55]
	v_mov_b64_e32 v[22:23], v[50:51]
	v_mov_b64_e32 v[26:27], v[46:47]
	v_mov_b64_e32 v[30:31], v[42:43]
	v_mov_b64_e32 v[34:35], v[38:39]
	v_mov_b64_e32 v[8:9], v[68:69]
	v_mov_b64_e32 v[12:13], v[64:65]
	v_mov_b64_e32 v[16:17], v[60:61]
	v_mov_b64_e32 v[20:21], v[56:57]
	v_mov_b64_e32 v[24:25], v[52:53]
	v_mov_b64_e32 v[28:29], v[48:49]
	v_mov_b64_e32 v[32:33], v[44:45]
	v_mov_b64_e32 v[36:37], v[40:41]
